# mla_finalize token loop: the next token's seven row loads are issued mid-iteration (right after the current raw rows are unpacked) so their latency is covered by the remaining work
# speedup vs baseline: 1.0120x; 1.0120x over previous
; DI float bf2f(u16 v) { return __uint_as_float(((unsigned)v) << 16); }
; DI void mla_finalize(const P& p, char* smem, int vb, int nvb) {
;   const int tid_ = get_tid();
;   const int lane = tid_ & 63, wave = tid_ >> 6;
;   const u16* z = (const u16*)(p.ws + OFF_REGB);
;   u16* Q = (u16*)(p.ws + OFF_QB);
;   u16* Kb = (u16*)(p.ws + OFF_KB);
;   u16* KV = (u16*)(p.ws + OFF_REGA);
;   float* sq = (float*)smem + wave * 1824;
;   float* skv = sq + 768;
;   float* skr = skv + 1024;
;   const int h = lane >> 3, sub = lane & 7;
;   const float QSCALE = 0.10206207261596575f * LOG2E;
;   float qn[12], kn[12];
; #pragma unroll
;   for (int j = 0; j < 12; ++j) { qn[j] = p.ev_q_norm[sub + 8 * j]; kn[j] = p.ev_k_norm[sub + 8 * j]; }
;   for (int t = vb * 4 + wave; t < T; t += nvb * 4) {
;     float f[8];
;     {
;       uint4 v = *(const uint4*)(Q + (size_t)t * 768 + lane * 8);
;       unpack8(v, f);
; #pragma unroll
;       for (int j = 0; j < 8; ++j) sq[lane * 8 + j] = f[j];
;       if (lane < 32) {
;         v = *(const uint4*)(Q + (size_t)t * 768 + (lane + 64) * 8);
;         unpack8(v, f);
; #pragma unroll
;         for (int j = 0; j < 8; ++j) sq[(lane + 64) * 8 + j] = f[j];
;       }
;     }
;     uint4 kv0 = *(const uint4*)(KV + (size_t)t * 1024 + lane * 8);
;     uint4 kv1 = *(const uint4*)(KV + (size_t)t * 1024 + (lane + 64) * 8);
;     unpack8(kv0, f);
; #pragma unroll
;     for (int j = 0; j < 8; ++j) skv[lane * 8 + j] = f[j];
;     unpack8(kv1, f);
; #pragma unroll
;     for (int j = 0; j < 8; ++j) skv[(lane + 64) * 8 + j] = f[j];
;     if (lane < 32) skr[lane] = bf2f(z[(size_t)t * EVEN_IN + 640 + lane]);
;     float ssq = 0.f, sskv = 0.f;
;     if (lane < 48) {
;       uint4 v = *(const uint4*)(z + (size_t)t * EVEN_IN + lane * 8);
.LBB0_1033:
	s_or_b64 exec, exec, s[0:1]
	v_mov_b32_e32 v1, v132
	s_barrier
	v_readlane_b32 s0, v218, 11
	v_ashrrev_i32_e32 v0, 6, v1
	v_readlane_b32 s1, v218, 12
	v_add_u32_e32 v72, s0, v0
	s_movk_i32 s0, 0x4800
	v_cmp_gt_i32_e32 vcc, s0, v72
	s_and_saveexec_b64 s[4:5], vcc
	v_readlane_b32 s54, v218, 44
	s_cbranch_execz .LBB0_1052
	v_readlane_b32 s76, v223, 6
	v_readlane_b32 s77, v223, 7
	v_readlane_b32 s78, v223, 8
	v_readlane_b32 s79, v223, 9
	v_readlane_b32 s80, v223, 10
	v_readlane_b32 s81, v223, 11
	v_readlane_b32 s82, v223, 12
	v_readlane_b32 s83, v223, 13
	v_readlane_b32 s84, v223, 14
	v_readlane_b32 s85, v223, 15
	v_readlane_b32 s86, v223, 16
	v_readlane_b32 s87, v223, 17
	v_and_b32_e32 v2, 7, v1
	v_readlane_b32 s72, v223, 38
	v_lshlrev_b32_e32 v3, 2, v2
	v_readlane_b32 s90, v223, 20
	v_readlane_b32 s91, v223, 21
	v_readlane_b32 s73, v223, 39
	s_movk_i32 s0, 0x1c80
	v_mul_lo_u32 v6, v0, s0
	v_add_u32_e32 v6, 0, v6
	v_cmp_lt_i32_e32 vcc, v137, v139
	global_load_dword v17, v3, s[90:91] offset:352
	global_load_dword v19, v3, s[72:73] offset:96
	global_load_dword v18, v3, s[72:73] offset:64
	global_load_dword v21, v3, s[72:73] offset:32
	global_load_dword v20, v3, s[72:73]
	global_load_dword v16, v3, s[90:91] offset:320
	global_load_dword v23, v3, s[90:91] offset:288
	global_load_dword v22, v3, s[90:91] offset:256
	global_load_dword v25, v3, s[72:73] offset:352
	global_load_dword v24, v3, s[72:73] offset:320
	global_load_dword v27, v3, s[72:73] offset:288
	global_load_dword v26, v3, s[72:73] offset:256
	global_load_dword v29, v3, s[72:73] offset:224
	global_load_dword v28, v3, s[72:73] offset:192
	global_load_dword v31, v3, s[72:73] offset:160
	global_load_dword v30, v3, s[72:73] offset:128
	global_load_dword v33, v3, s[90:91] offset:224
	global_load_dword v32, v3, s[90:91] offset:192
	global_load_dword v35, v3, s[90:91] offset:160
	global_load_dword v34, v3, s[90:91] offset:128
	global_load_dword v37, v3, s[90:91] offset:96
	global_load_dword v36, v3, s[90:91] offset:64
	global_load_dword v39, v3, s[90:91] offset:32
	global_load_dword v38, v3, s[90:91]
	v_add_u32_e32 v73, v6, v3
	v_cndmask_b32_e32 v3, v136, v137, vcc
	v_cmp_lt_i32_e32 vcc, v140, v139
	v_lshlrev_b32_e32 v75, 2, v3
	s_mov_b32 s15, 0xc2fc0000
	v_cndmask_b32_e32 v3, v136, v140, vcc
	v_cmp_lt_i32_e32 vcc, v141, v139
	v_lshlrev_b32_e32 v76, 2, v3
	v_and_b32_e32 v4, 63, v1
	v_cndmask_b32_e32 v3, v136, v141, vcc
	v_cmp_lt_i32_e32 vcc, v142, v139
	v_lshlrev_b32_e32 v77, 2, v3
	v_bfe_u32 v5, v1, 3, 3
	v_cndmask_b32_e32 v3, v136, v142, vcc
	v_cmp_lt_i32_e32 vcc, v143, v139
	v_lshlrev_b32_e32 v78, 2, v3
	v_cmp_lt_i32_e64 s[40:41], v144, v139
	v_cndmask_b32_e32 v3, v136, v143, vcc
	v_lshlrev_b32_e32 v79, 2, v3
	v_cvt_f32_ubyte0_e32 v3, v2
	v_mul_f32_e32 v7, 0xbfd49a78, v3
	v_cmp_gt_f32_e32 vcc, s15, v7
	v_and_b32_e32 v1, 8, v1
	v_cmp_ne_u32_e64 s[42:43], 0, v1
	v_cndmask_b32_e32 v7, 0, v145, vcc
	v_fmac_f32_e32 v7, 0xbfd49a78, v3
	v_exp_f32_e32 v3, v7
	v_cndmask_b32_e64 v7, v136, v144, s[40:41]
	v_cmp_eq_u32_e64 s[40:41], 0, v1
	v_or_b32_e32 v1, v138, v2
	v_readlane_b32 s16, v218, 11
	v_lshlrev_b32_e32 v82, 2, v1
	v_ashrrev_i32_e32 v1, 31, v0
	v_readlane_b32 s17, v218, 12
	v_lshlrev_b32_e32 v80, 2, v7
	v_cndmask_b32_e32 v7, 0, v146, vcc
	v_lshl_add_u64 v[0:1], s[16:17], 0, v[0:1]
	v_ldexp_f32 v81, v3, v7
	v_mad_u64_u32 v[2:3], s[16:17], v0, s7, 0
	v_mad_i32_i24 v3, v1, s7, v3
	v_lshl_or_b32 v2, v4, 1, v2
	s_mov_b64 s[16:17], 0x5872500
	v_lshl_add_u64 v[40:41], v[2:3], 0, s[16:17]
	v_lshlrev_b32_e32 v2, 4, v4
	v_mov_b32_e32 v3, v96
	s_movk_i32 s15, 0x600
	v_lshl_add_u32 v74, v4, 5, v6
	v_cmp_gt_u32_e64 s[0:1], 32, v4
	v_mul_i32_i24_e32 v6, 0xffffffe4, v4
	v_cmp_gt_u32_e64 s[38:39], 48, v4
	v_mul_u32_u24_e32 v7, 0x180, v5
	v_lshlrev_b32_e32 v8, 9, v5
	v_mad_u64_u32 v[42:43], s[16:17], v0, s15, v[2:3]
	v_mad_u64_u32 v[4:5], s[16:17], v0, s7, v[2:3]
	v_mad_i32_i24 v43, v1, s15, v43
	v_mad_i32_i24 v5, v1, s7, v5
	s_mov_b64 s[16:17], 0x5872300
	v_lshlrev_b64 v[0:1], 11, v[0:1]
	v_lshl_add_u64 v[44:45], v[4:5], 0, s[16:17]
	v_or_b32_e32 v0, v0, v2
	s_mov_b64 s[16:17], 0x3472400
	v_or_b32_e32 v83, 32, v82
	v_lshl_add_u64 v[46:47], v[0:1], 0, s[16:17]
	s_mov_b64 s[48:49], 0
	v_add_u32_e32 v84, v74, v6
	v_add_u32_e32 v85, v73, v8
	v_add_u32_e32 v86, v73, v7
	v_readlane_b32 s88, v223, 18
	v_readlane_b32 s89, v223, 19
	v_readlane_b32 s74, v223, 40
	v_readlane_b32 s75, v223, 41
	v_readlane_b32 s76, v223, 42
	v_readlane_b32 s77, v223, 43
	v_readlane_b32 s78, v223, 44
	v_readlane_b32 s79, v223, 45
	v_readlane_b32 s80, v223, 46
	v_readlane_b32 s81, v223, 47
	v_readlane_b32 s82, v223, 48
	v_readlane_b32 s83, v223, 49
	v_readlane_b32 s84, v223, 50
	v_readlane_b32 s85, v223, 51
	v_readlane_b32 s86, v223, 52
	v_readlane_b32 s87, v223, 53
	v_lshl_add_u64 v[250:251], s[70:71], 0, v[42:43]
	v_add_co_u32_e32 v250, vcc, 0xbb72000, v250
	s_nop 1
	v_addc_co_u32_e32 v251, vcc, 0, v251, vcc
	global_load_dwordx4 v[224:227], v[250:251], off
	v_lshl_add_u64 v[252:253], s[70:71], 0, v[46:47]
	global_load_dwordx4 v[232:235], v[252:253], off offset:-1024
	global_load_dwordx4 v[236:239], v[252:253], off
	v_lshl_add_u64 v[252:253], s[70:71], 0, v[40:41]
	v_lshl_add_u64 v[254:255], s[70:71], 0, v[44:45]
	s_and_saveexec_b64 s[44:45], s[0:1]
	global_load_dwordx4 v[228:231], v[250:251], off offset:1024
	global_load_ushort v240, v[252:253], off
	global_load_dwordx4 v[246:249], v[254:255], off
	s_or_b64 exec, exec, s[44:45]
	s_and_saveexec_b64 s[44:45], s[38:39]
	global_load_dwordx4 v[242:245], v[254:255], off offset:-768
	s_or_b64 exec, exec, s[44:45]
	s_waitcnt vmcnt(0)
	s_branch .LBB0_1036

; DI float bf2f(u16 v) { return __uint_as_float(((unsigned)v) << 16); }
; DI void mla_finalize(const P& p, char* smem, int vb, int nvb) {
;     ...
;   for (int t = vb * 4 + wave; t < T; t += nvb * 4) {
;     float f[8];
;     {
;       uint4 v = *(const uint4*)(Q + (size_t)t * 768 + lane * 8);
;       unpack8(v, f);
; #pragma unroll
;       for (int j = 0; j < 8; ++j) sq[lane * 8 + j] = f[j];
;       if (lane < 32) {
;         v = *(const uint4*)(Q + (size_t)t * 768 + (lane + 64) * 8);
;         unpack8(v, f);
; #pragma unroll
;         for (int j = 0; j < 8; ++j) sq[(lane + 64) * 8 + j] = f[j];
;       }
;     }
;     uint4 kv0 = *(const uint4*)(KV + (size_t)t * 1024 + lane * 8);
;     uint4 kv1 = *(const uint4*)(KV + (size_t)t * 1024 + (lane + 64) * 8);
;     unpack8(kv0, f);
; #pragma unroll
;     for (int j = 0; j < 8; ++j) skv[lane * 8 + j] = f[j];
;     unpack8(kv1, f);
; #pragma unroll
;     for (int j = 0; j < 8; ++j) skv[(lane + 64) * 8 + j] = f[j];
;     if (lane < 32) skr[lane] = bf2f(z[(size_t)t * EVEN_IN + 640 + lane]);
;     float ssq = 0.f, sskv = 0.f;
;     if (lane < 48) {
;       uint4 v = *(const uint4*)(z + (size_t)t * EVEN_IN + lane * 8);
;       unpack8(v, f);
; #pragma unroll
;       for (int j = 0; j < 8; ++j) ssq += f[j] * f[j];
;     }
;     if (lane < 32) {
;       uint4 v = *(const uint4*)(z + (size_t)t * EVEN_IN + 384 + lane * 8);
;       unpack8(v, f);
; #pragma unroll
;       for (int j = 0; j < 8; ++j) sskv += f[j] * f[j];
;     }
;     ssq = wave_sum(ssq);
;     sskv = wave_sum(sskv);
;     const float rq = rsqrtf(ssq * (1.f / 384.f) + EPS), rkv = rsqrtf(sskv * (1.f / 256.f) + EPS);
;     const bool lat = t < LAT;
;     const int pos = t & 2047;
;     float cs = 1.f, sn = 0.f;
;     if (lat) {
;       const int fi = lane & 7;
;       const float inv = exp2f(-(float)fi * (13.287712379549449f / 8.f));
;       const float pc = (lane & 8) ? (float)(pos & 63) : (float)(pos >> 6);
;       float rev = pc * inv * 0.15915494309189535f;
;       rev -= floorf(rev);
;       cs = __builtin_amdgcn_cosf(rev);
;       sn = __builtin_amdgcn_sinf(rev);
;     }
;     const float c0 = __shfl(cs, sub), s0 = __shfl(sn, sub), c1 = __shfl(cs, sub + 8), s1 = __shfl(sn, sub + 8);
.LBB0_1036:
	s_waitcnt vmcnt(25)
	v_lshl_add_u64 v[48:49], s[70:71], 0, v[42:43]
	v_add_co_u32_e32 v0, vcc, 0xbb72000, v48
	s_nop 1
	v_addc_co_u32_e32 v1, vcc, 0, v49, vcc
	s_waitcnt vmcnt(12)
	v_lshlrev_b32_e32 v10, 16, v227
	v_lshlrev_b32_e32 v8, 16, v226
	v_and_b32_e32 v11, 0xffff0000, v227
	v_and_b32_e32 v9, 0xffff0000, v226
	v_lshlrev_b32_e32 v6, 16, v225
	v_lshlrev_b32_e32 v4, 16, v224
	v_and_b32_e32 v7, 0xffff0000, v225
	v_and_b32_e32 v5, 0xffff0000, v224
	ds_write_b128 v74, v[8:11] offset:16
	ds_write_b128 v74, v[4:7]
	s_and_saveexec_b64 s[44:45], s[0:1]
	s_cbranch_execz .LBB0_1038
	v_add_co_u32_e32 v0, vcc, 0xbb72000, v48
	s_nop 1
	v_addc_co_u32_e32 v1, vcc, 0, v49, vcc
	s_waitcnt vmcnt(9)
	v_lshlrev_b32_e32 v10, 16, v231
	v_lshlrev_b32_e32 v8, 16, v230
	v_and_b32_e32 v11, 0xffff0000, v231
	v_and_b32_e32 v9, 0xffff0000, v230
	v_lshlrev_b32_e32 v6, 16, v229
	v_lshlrev_b32_e32 v4, 16, v228
	v_and_b32_e32 v7, 0xffff0000, v229
	v_and_b32_e32 v5, 0xffff0000, v228
	ds_write_b128 v74, v[8:11] offset:2064
	ds_write_b128 v74, v[4:7] offset:2048
.LBB0_1038:
	s_or_b64 exec, exec, s[44:45]
	v_lshl_add_u64 v[50:51], s[70:71], 0, v[46:47]
	s_waitcnt vmcnt(11)
	v_lshlrev_b32_e32 v0, 16, v232
	v_and_b32_e32 v1, 0xffff0000, v232
	v_lshlrev_b32_e32 v2, 16, v233
	v_and_b32_e32 v3, 0xffff0000, v233
	v_lshlrev_b32_e32 v4, 16, v234
	v_and_b32_e32 v5, 0xffff0000, v234
	v_lshlrev_b32_e32 v6, 16, v235
	v_and_b32_e32 v7, 0xffff0000, v235
	s_waitcnt vmcnt(10)
	v_lshlrev_b32_e32 v8, 16, v236
	v_and_b32_e32 v9, 0xffff0000, v236
	v_lshlrev_b32_e32 v10, 16, v237
	v_and_b32_e32 v11, 0xffff0000, v237
	v_lshlrev_b32_e32 v12, 16, v238
	v_and_b32_e32 v13, 0xffff0000, v238
	v_lshlrev_b32_e32 v14, 16, v239
	v_and_b32_e32 v15, 0xffff0000, v239
	ds_write_b128 v74, v[0:3] offset:3072
	ds_write_b128 v74, v[4:7] offset:3088
	ds_write_b128 v74, v[8:11] offset:5120
	ds_write_b128 v74, v[12:15] offset:5136
	s_and_saveexec_b64 s[44:45], s[0:1]
	s_cbranch_execz .LBB0_1040
	v_lshl_add_u64 v[52:53], s[70:71], 0, v[40:41]
	s_waitcnt vmcnt(8)
	v_lshlrev_b32_e32 v52, 16, v240
	ds_write_b32 v84, v52 offset:7168
.LBB0_1040:
	s_or_b64 exec, exec, s[44:45]
	v_mov_b32_e32 v52, 0
	v_lshl_add_u64 v[54:55], s[70:71], 0, v[44:45]
	v_mov_b32_e32 v53, 0
	s_and_saveexec_b64 s[44:45], s[38:39]
	s_cbranch_execz .LBB0_1042
	s_waitcnt vmcnt(6)
	v_lshlrev_b32_e32 v60, 16, v242
	v_and_b32_e32 v61, 0xffff0000, v242
	v_lshlrev_b32_e32 v63, 16, v243
	v_and_b32_e32 v62, 0xffff0000, v243
	v_lshlrev_b32_e32 v57, 16, v244
	v_and_b32_e32 v56, 0xffff0000, v244
	v_lshlrev_b32_e32 v65, 16, v245
	v_and_b32_e32 v64, 0xffff0000, v245
	v_pk_mul_f32 v[58:59], v[60:61], v[60:61]
	v_pk_mul_f32 v[60:61], v[62:63], v[62:63]
	v_add_f32_e32 v53, v58, v59
	v_add_f32_e32 v53, v53, v61
	v_pk_mul_f32 v[56:57], v[56:57], v[56:57]
	v_add_f32_e32 v53, v60, v53
	v_add_f32_e32 v53, v57, v53
	v_pk_mul_f32 v[62:63], v[64:65], v[64:65]
	v_add_f32_e32 v53, v56, v53
	v_add_f32_e32 v53, v63, v53
	v_add_f32_e32 v53, v62, v53
.LBB0_1042:
	s_or_b64 exec, exec, s[44:45]
	s_and_saveexec_b64 s[44:45], s[0:1]
	s_cbranch_execz .LBB0_1044
	s_waitcnt vmcnt(6)
	v_lshlrev_b32_e32 v58, 16, v246
	v_and_b32_e32 v59, 0xffff0000, v246
	v_lshlrev_b32_e32 v61, 16, v247
	v_and_b32_e32 v60, 0xffff0000, v247
	v_lshlrev_b32_e32 v55, 16, v248
	v_and_b32_e32 v54, 0xffff0000, v248
	v_lshlrev_b32_e32 v63, 16, v249
	v_and_b32_e32 v62, 0xffff0000, v249
	v_pk_mul_f32 v[56:57], v[58:59], v[58:59]
	v_pk_mul_f32 v[58:59], v[60:61], v[60:61]
	v_add_f32_e32 v52, v56, v57
	v_add_f32_e32 v52, v52, v59
	v_pk_mul_f32 v[54:55], v[54:55], v[54:55]
	v_add_f32_e32 v52, v58, v52
	v_add_f32_e32 v52, v55, v52
	v_pk_mul_f32 v[60:61], v[62:63], v[62:63]
	v_add_f32_e32 v52, v54, v52
	v_add_f32_e32 v52, v61, v52
	v_add_f32_e32 v52, v60, v52
.LBB0_1044:
	s_or_b64 exec, exec, s[44:45]
	v_lshl_add_u64 v[250:251], s[70:71], 0, v[42:43]
	v_readlane_b32 s100, v218, 15
	v_readlane_b32 s101, v218, 16
	s_nop 3
	v_lshl_add_u64 v[250:251], v[250:251], 0, s[100:101]
	v_add_co_u32_e32 v250, vcc, 0xbb72000, v250
	s_nop 1
	v_addc_co_u32_e32 v251, vcc, 0, v251, vcc
	global_load_dwordx4 v[224:227], v[250:251], off
	v_lshl_add_u64 v[252:253], s[70:71], 0, v[46:47]
	v_readlane_b32 s100, v218, 23
	v_readlane_b32 s101, v218, 24
	s_nop 3
	v_lshl_add_u64 v[252:253], v[252:253], 0, s[100:101]
	global_load_dwordx4 v[232:235], v[252:253], off offset:-1024
	global_load_dwordx4 v[236:239], v[252:253], off
	v_lshl_add_u64 v[252:253], s[70:71], 0, v[40:41]
	v_readlane_b32 s100, v218, 13
	v_readlane_b32 s101, v218, 14
	s_nop 3
	v_lshl_add_u64 v[252:253], v[252:253], 0, s[100:101]
	v_lshl_add_u64 v[254:255], s[70:71], 0, v[44:45]
	v_readlane_b32 s100, v218, 13
	v_readlane_b32 s101, v218, 14
	s_nop 3
	v_lshl_add_u64 v[254:255], v[254:255], 0, s[100:101]
	s_and_saveexec_b64 s[44:45], s[0:1]
	global_load_dwordx4 v[228:231], v[250:251], off offset:1024
	global_load_ushort v240, v[252:253], off
	global_load_dwordx4 v[246:249], v[254:255], off
	s_or_b64 exec, exec, s[44:45]
	s_and_saveexec_b64 s[44:45], s[38:39]
	global_load_dwordx4 v[242:245], v[254:255], off offset:-768
	s_or_b64 exec, exec, s[44:45]
	v_cmp_gt_i32_e64 s[44:45], s8, v72
	v_mov_b32_e32 v67, 1.0
	v_mov_b32_e32 v69, 0
	v_add_f32_dpp v52, v52, v52 quad_perm:[1,0,3,2] row_mask:0xf bank_mask:0xf
	v_add_f32_dpp v53, v53, v53 quad_perm:[1,0,3,2] row_mask:0xf bank_mask:0xf
	s_nop 0
	v_add_f32_dpp v52, v52, v52 quad_perm:[2,3,0,1] row_mask:0xf bank_mask:0xf
	v_add_f32_dpp v53, v53, v53 quad_perm:[2,3,0,1] row_mask:0xf bank_mask:0xf
	s_nop 0
	v_add_f32_dpp v52, v52, v52 row_half_mirror row_mask:0xf bank_mask:0xf
	v_add_f32_dpp v53, v53, v53 row_half_mirror row_mask:0xf bank_mask:0xf
	s_nop 0
	v_add_f32_dpp v52, v52, v52 row_mirror row_mask:0xf bank_mask:0xf
	v_add_f32_dpp v53, v53, v53 row_mirror row_mask:0xf bank_mask:0xf
	s_nop 0
	v_add_f32_dpp v52, v52, v52 row_bcast:15 row_mask:0xa bank_mask:0xf
	v_add_f32_dpp v53, v53, v53 row_bcast:15 row_mask:0xa bank_mask:0xf
	s_nop 0
	v_add_f32_dpp v52, v52, v52 row_bcast:31 row_mask:0xc bank_mask:0xf
	v_add_f32_dpp v53, v53, v53 row_bcast:31 row_mask:0xc bank_mask:0xf
	s_nop 0
	s_nop 0
	v_readlane_b32 s100, v52, 63
	v_readlane_b32 s101, v53, 63
	s_nop 3
	v_mov_b32_e32 v52, s100
	v_mov_b32_e32 v53, s101
	s_and_saveexec_b64 s[46:47], s[44:45]
	s_cbranch_execz .LBB0_1046
	v_and_b32_e32 v56, 63, v72
	v_bfe_u32 v57, v72, 6, 5
	v_cndmask_b32_e64 v56, v56, v57, s[40:41]
	v_cvt_f32_ubyte0_e32 v56, v56
	v_mul_f32_e32 v56, v81, v56
	v_mul_f32_e32 v57, 0.15915494, v56
	v_floor_f32_e32 v57, v57
	v_fma_f32 v56, v56, 0.15915494, -v57
	v_cos_f32_e32 v67, v56
	v_sin_f32_e32 v69, v56
